# scan step head: only the w_k fragment reads precede the first MFMAs, q_dec fragment reads interleaved behind them
# speedup vs baseline: 1.0092x; 1.0010x over previous
.Lscan_compute:
	s_mul_i32 s11, s11, 0x12000
	s_add_i32 s6, s11, 0
	v_add_u32_e32 v0, s6, v58
	v_add_u32_e32 v2, s6, v59
	v_add_u32_e32 v3, s6, v60
	v_add_u32_e32 v142, s6, v61
	ds_read_b128 v[62:65], v0
	ds_read_b128 v[66:69], v0 offset:4096
	ds_read_b128 v[70:73], v2
	ds_read_b128 v[74:77], v2 offset:4096
	ds_read_b128 v[78:81], v3
	ds_read_b128 v[82:85], v3 offset:4096
	ds_read_b128 v[86:89], v142
	ds_read_b128 v[90:93], v142 offset:4096
	ds_read_b128 v[94:97], v0 offset:8192
	ds_read_b128 v[98:101], v0 offset:12288
	ds_read_b128 v[102:105], v2 offset:8192
	ds_read_b128 v[106:109], v2 offset:12288
	ds_read_b128 v[110:113], v3 offset:8192
	ds_read_b128 v[114:117], v3 offset:12288
	ds_read_b128 v[118:121], v142 offset:8192
	ds_read_b128 v[122:125], v142 offset:12288
	v_mov_b32_e32 v215, v0
	v_mov_b32_e32 v221, v2
	v_mov_b32_e32 v248, v3
	v_mov_b32_e32 v249, v142
	v_cvt_pk_bf16_f32 v202, v12, v13
	v_cvt_pk_bf16_f32 v203, v14, v15
	v_cvt_pk_bf16_f32 v204, v4, v5
	v_cvt_pk_bf16_f32 v205, v6, v7
	v_cvt_pk_bf16_f32 v206, v8, v9
	v_cvt_pk_bf16_f32 v207, v10, v11
	v_cvt_pk_bf16_f32 v208, v16, v17
	v_cvt_pk_bf16_f32 v209, v18, v19
	v_cvt_pk_bf16_f32 v210, v20, v21
	v_cvt_pk_bf16_f32 v211, v22, v23
	v_cvt_pk_bf16_f32 v212, v24, v25
	v_cvt_pk_bf16_f32 v213, v26, v27
	v_cvt_pk_bf16_f32 v222, v28, v29
	v_cvt_pk_bf16_f32 v223, v30, v31
	v_cvt_pk_bf16_f32 v224, v32, v33
	v_cvt_pk_bf16_f32 v225, v34, v35
	s_waitcnt lgkmcnt(15)
	v_mfma_f32_16x16x32_bf16 v[62:65], v[62:65], v[202:205], 0
	v_add3_u32 v0, s6, v56, v57
	v_add_u32_e32 v145, s6, v55
	v_add_u32_e32 v159, s6, v54
	s_waitcnt lgkmcnt(14)
	v_mfma_f32_16x16x32_bf16 v[66:69], v[66:69], v[202:205], 0
	ds_read2st64_b32 v[2:3], v0 offset0:224 offset1:225
	ds_read2st64_b32 v[142:143], v0 offset0:226 offset1:227
	s_waitcnt lgkmcnt(15)
	v_mfma_f32_16x16x32_bf16 v[62:65], v[70:73], v[206:209], v[62:65]
	ds_read_b128 v[126:129], v215 offset:16384
	ds_read_b128 v[130:133], v215 offset:20480
	s_waitcnt lgkmcnt(15)
	v_mfma_f32_16x16x32_bf16 v[66:69], v[74:77], v[206:209], v[66:69]
	ds_read_b128 v[134:137], v221 offset:16384
	ds_read_b128 v[138:141], v221 offset:20480
	s_waitcnt lgkmcnt(13)
	v_mfma_f32_16x16x32_bf16 v[70:73], v[94:97], v[202:205], 0
	ds_read_b128 v[146:149], v248 offset:16384
	ds_read_b128 v[154:157], v248 offset:20480
	v_mfma_f32_16x16x32_bf16 v[62:65], v[78:81], v[210:213], v[62:65]
	ds_read_b128 v[162:165], v249 offset:16384
	ds_read_b128 v[78:81], v145 offset:49152
	v_mfma_f32_16x16x32_bf16 v[66:69], v[82:85], v[210:213], v[66:69]
	ds_read_b128 v[166:169], v249 offset:20480
	ds_read_b128 v[170:173], v215 offset:24576
	s_waitcnt lgkmcnt(15)
	v_mfma_f32_16x16x32_bf16 v[74:77], v[98:101], v[202:205], 0
	ds_read_b128 v[174:177], v215 offset:28672
	ds_read_b128 v[178:181], v221 offset:24576
	v_mfma_f32_16x16x32_bf16 v[70:73], v[102:105], v[206:209], v[70:73]
	ds_read_b128 v[182:185], v221 offset:28672
	ds_read_b128 v[186:189], v248 offset:24576
	v_add_u32_e32 v102, 0xe000, v0
	v_mfma_f32_16x16x32_bf16 v[62:65], v[86:89], v[222:225], v[62:65]
	ds_read_b128 v[190:193], v248 offset:28672
	v_mfma_f32_16x16x32_bf16 v[66:69], v[90:93], v[222:225], v[66:69]
	ds_read_b128 v[194:197], v249 offset:24576
	v_mfma_f32_16x16x32_bf16 v[74:77], v[106:109], v[206:209], v[74:77]
	ds_read_b128 v[198:201], v249 offset:28672
	ds_read_b128 v[82:85], v159 offset:49152
	ds_read2st64_b32 v[226:227], v0 offset0:240 offset1:241
	ds_read2st64_b32 v[228:229], v0 offset0:242 offset1:243
	ds_read_b128 v[86:89], v145 offset:51200
	ds_read_b128 v[90:93], v159 offset:51200
	ds_read2st64_b32 v[230:231], v102 offset0:32 offset1:33
	ds_read2st64_b32 v[232:233], v102 offset0:34 offset1:35
	ds_read_b128 v[94:97], v145 offset:53248
	ds_read_b128 v[98:101], v159 offset:53248
	ds_read2st64_b32 v[234:235], v102 offset0:48 offset1:49
	ds_read2st64_b32 v[236:237], v102 offset0:50 offset1:51
	ds_read_b128 v[102:105], v145 offset:55296
	ds_read_b128 v[106:109], v159 offset:55296
	v_mfma_f32_16x16x32_bf16 v[70:73], v[110:113], v[210:213], v[70:73]
	s_waitcnt lgkmcnt(15)
	v_mfma_f32_16x16x32_bf16 v[74:77], v[114:117], v[210:213], v[74:77]
	v_mfma_f32_16x16x32_bf16 v[70:73], v[118:121], v[222:225], v[70:73]
	v_mfma_f32_16x16x32_bf16 v[74:77], v[122:125], v[222:225], v[74:77]
	v_mfma_f32_16x16x32_bf16 v[110:113], v[126:129], v[202:205], 0
	v_mfma_f32_16x16x32_bf16 v[114:117], v[130:133], v[202:205], 0
	v_mfma_f32_16x16x32_bf16 v[118:121], v[170:173], v[202:205], 0
	v_mfma_f32_16x16x32_bf16 v[122:125], v[174:177], v[202:205], 0
	v_mfma_f32_16x16x32_bf16 v[110:113], v[134:137], v[206:209], v[110:113]
	v_mfma_f32_16x16x32_bf16 v[114:117], v[138:141], v[206:209], v[114:117]
	v_mfma_f32_16x16x32_bf16 v[118:121], v[178:181], v[206:209], v[118:121]
	v_mfma_f32_16x16x32_bf16 v[122:125], v[182:185], v[206:209], v[122:125]
	v_mfma_f32_16x16x32_bf16 v[110:113], v[146:149], v[210:213], v[110:113]
	v_mfma_f32_16x16x32_bf16 v[114:117], v[154:157], v[210:213], v[114:117]
	v_mfma_f32_16x16x32_bf16 v[118:121], v[186:189], v[210:213], v[118:121]
	v_mfma_f32_16x16x32_bf16 v[122:125], v[190:193], v[210:213], v[122:125]
	v_mfma_f32_16x16x32_bf16 v[110:113], v[162:165], v[222:225], v[110:113]
	v_mfma_f32_16x16x32_bf16 v[114:117], v[166:169], v[222:225], v[114:117]
	s_waitcnt lgkmcnt(14)
	v_mfma_f32_16x16x32_bf16 v[118:121], v[194:197], v[222:225], v[118:121]
	s_waitcnt lgkmcnt(13)
	v_mfma_f32_16x16x32_bf16 v[122:125], v[198:201], v[222:225], v[122:125]
	ds_read_b128 v[126:129], v145 offset:32768
	ds_read_b128 v[130:133], v159 offset:32768
	ds_read_b128 v[134:137], v145 offset:34816
	ds_read_b128 v[138:141], v159 offset:34816
	ds_read_b128 v[146:149], v145 offset:36864
	ds_read_b128 v[154:157], v159 offset:36864
	ds_read_b128 v[162:165], v145 offset:38912
	ds_read_b128 v[166:169], v159 offset:38912
	ds_read_b128 v[170:173], v145 offset:40960
	ds_read_b128 v[174:177], v159 offset:40960
	ds_read_b128 v[178:181], v145 offset:43008
	ds_read_b128 v[182:185], v159 offset:43008
	ds_read_b128 v[186:189], v145 offset:45056
	ds_read_b128 v[190:193], v159 offset:45056
	ds_read_b128 v[194:197], v145 offset:47104
	ds_read_b128 v[198:201], v159 offset:47104
	v_pk_add_f32 v[2:3], v[2:3], v[62:63] neg_lo:[0,1] neg_hi:[0,1]
	v_pk_add_f32 v[64:65], v[142:143], v[64:65] neg_lo:[0,1] neg_hi:[0,1]
	s_waitcnt lgkmcnt(14)
	v_pk_add_f32 v[66:67], v[226:227], v[66:67] neg_lo:[0,1] neg_hi:[0,1]
	v_pk_add_f32 v[68:69], v[228:229], v[68:69] neg_lo:[0,1] neg_hi:[0,1]
	v_pk_add_f32 v[70:71], v[230:231], v[70:71] neg_lo:[0,1] neg_hi:[0,1]
	v_cvt_pk_bf16_f32 v62, v2, v3
	v_cvt_pk_bf16_f32 v63, v64, v65
	v_cvt_pk_bf16_f32 v64, v66, v67
	v_cvt_pk_bf16_f32 v65, v68, v69
	v_pk_add_f32 v[142:143], v[232:233], v[72:73] neg_lo:[0,1] neg_hi:[0,1]
	v_cvt_pk_bf16_f32 v66, v70, v71
	v_mfma_f32_16x16x32_bf16 v[70:73], v[78:81], v[62:65], v[110:113]
	v_readlane_b32 s6, v37, s10
	v_pk_add_f32 v[74:75], v[234:235], v[74:75] neg_lo:[0,1] neg_hi:[0,1]
	v_pk_add_f32 v[76:77], v[236:237], v[76:77] neg_lo:[0,1] neg_hi:[0,1]
	v_pk_mul_f32 v[6:7], v[6:7], s[6:7] op_sel_hi:[1,0]
	v_pk_mul_f32 v[4:5], v[4:5], s[6:7] op_sel_hi:[1,0]
	v_cvt_pk_bf16_f32 v67, v142, v143
	v_cvt_pk_bf16_f32 v68, v74, v75
	v_cvt_pk_bf16_f32 v69, v76, v77
	s_waitcnt lgkmcnt(13)
	v_mfma_f32_16x16x32_bf16 v[2:5], v[134:137], v[62:65], v[4:7]
	v_mul_f32_e64 v14, v14, s6
	v_mul_f32_e64 v15, v15, s6
	v_pk_mul_f32 v[12:13], v[12:13], s[6:7] op_sel_hi:[1,0]
	v_pk_mul_f32 v[10:11], v[10:11], s[6:7] op_sel_hi:[1,0]
	v_mfma_f32_16x16x32_bf16 v[70:73], v[82:85], v[66:69], v[70:73]
	v_mul_f32_e64 v8, v8, s6
	v_mul_f32_e64 v9, v9, s6
	v_pk_mul_f32 v[18:19], v[18:19], s[6:7] op_sel_hi:[1,0]
	v_pk_mul_f32 v[16:17], v[16:17], s[6:7] op_sel_hi:[1,0]
	v_mfma_f32_16x16x32_bf16 v[74:77], v[86:89], v[62:65], v[114:117]
	v_mul_f32_e64 v22, v22, s6
	v_mul_f32_e64 v23, v23, s6
	s_nop 0
	v_cvt_pk_bf16_f32 v0, v70, s0
	v_pk_mul_f32 v[20:21], v[20:21], s[6:7] op_sel_hi:[1,0]
	s_waitcnt lgkmcnt(12)
	v_mfma_f32_16x16x32_bf16 v[4:7], v[138:141], v[66:69], v[2:5]
	v_mul_f32_e64 v26, v26, s6
	v_mul_f32_e64 v27, v27, s6
	v_pk_mul_f32 v[24:25], v[24:25], s[6:7] op_sel_hi:[1,0]
	v_pk_mul_f32 v[30:31], v[30:31], s[6:7] op_sel_hi:[1,0]
	v_add_u32_e32 v70, 0x1000, v38
	v_pk_mul_f32 v[28:29], v[28:29], s[6:7] op_sel_hi:[1,0]
	v_pk_mul_f32 v[34:35], v[34:35], s[6:7] op_sel_hi:[1,0]
	v_pk_mul_f32 v[32:33], v[32:33], s[6:7] op_sel_hi:[1,0]
	global_store_short v38, v0, s[2:3]
	v_cvt_pk_bf16_f32 v0, v71, s0
	global_store_short v70, v0, s[2:3] offset:2048
	v_add_u32_e32 v70, 0x3000, v38
	v_mfma_f32_16x16x32_bf16 v[74:77], v[90:93], v[66:69], v[74:77]
	v_cvt_pk_bf16_f32 v0, v72, s0
	global_store_short v70, v0, s[2:3]
	v_add_u32_e32 v70, 0x4000, v38
	v_cvt_pk_bf16_f32 v0, v73, s0
	global_store_short v70, v0, s[2:3] offset:2048
	v_add_u32_e32 v70, 0x18000, v38
	v_mfma_f32_16x16x32_bf16 v[78:81], v[94:97], v[62:65], v[118:121]
	v_cvt_pk_bf16_f32 v0, v74, s0
	global_store_short v70, v0, s[2:3]
	v_add_u32_e32 v70, 0x19000, v38
	v_mfma_f32_16x16x32_bf16 v[82:85], v[102:105], v[62:65], v[122:125]
	v_cvt_pk_bf16_f32 v0, v75, s0
	global_store_short v70, v0, s[2:3] offset:2048
	v_cvt_pk_bf16_f32 v0, v76, s0
	v_mfma_f32_16x16x32_bf16 v[12:15], v[126:129], v[62:65], v[12:15]
	s_waitcnt lgkmcnt(11)
	v_mfma_f32_16x16x32_bf16 v[8:11], v[146:149], v[62:65], v[8:11]
	s_waitcnt lgkmcnt(9)
	v_mfma_f32_16x16x32_bf16 v[16:19], v[162:165], v[62:65], v[16:19]
	s_waitcnt lgkmcnt(7)
	v_mfma_f32_16x16x32_bf16 v[20:23], v[170:173], v[62:65], v[20:23]
	s_waitcnt lgkmcnt(5)
	v_mfma_f32_16x16x32_bf16 v[24:27], v[178:181], v[62:65], v[24:27]
	s_waitcnt lgkmcnt(3)
	v_mfma_f32_16x16x32_bf16 v[28:31], v[186:189], v[62:65], v[28:31]
	s_waitcnt lgkmcnt(1)
	v_mfma_f32_16x16x32_bf16 v[32:35], v[194:197], v[62:65], v[32:35]
	v_add_u32_e32 v62, 0x1b000, v38
	v_mfma_f32_16x16x32_bf16 v[78:81], v[98:101], v[66:69], v[78:81]
	global_store_short v62, v0, s[2:3]
	v_add_u32_e32 v62, 0x1c000, v38
	v_cvt_pk_bf16_f32 v0, v77, s0
	global_store_short v62, v0, s[2:3] offset:2048
	v_add_u32_e32 v62, 0x30000, v38
	v_cvt_pk_bf16_f32 v0, v78, s0
	global_store_short v62, v0, s[2:3]
	v_add_u32_e32 v62, 0x31000, v38
	v_cvt_pk_bf16_f32 v0, v79, s0
	global_store_short v62, v0, s[2:3] offset:2048
	v_add_u32_e32 v62, 0x33000, v38
	v_mfma_f32_16x16x32_bf16 v[82:85], v[106:109], v[66:69], v[82:85]
	v_cvt_pk_bf16_f32 v0, v80, s0
	global_store_short v62, v0, s[2:3]
	v_add_u32_e32 v62, 0x34000, v38
	v_cvt_pk_bf16_f32 v0, v81, s0
	global_store_short v62, v0, s[2:3] offset:2048
	v_add_u32_e32 v62, 0x48000, v38
	v_cvt_pk_bf16_f32 v0, v82, s0
	global_store_short v62, v0, s[2:3]
	v_add_u32_e32 v62, 0x49000, v38
	v_cvt_pk_bf16_f32 v0, v83, s0
	global_store_short v62, v0, s[2:3] offset:2048
	v_add_u32_e32 v62, 0x4b000, v38
	v_cvt_pk_bf16_f32 v0, v84, s0
	v_add_u32_e32 v2, 0x4c000, v38
	global_store_short v62, v0, s[2:3]
	v_cvt_pk_bf16_f32 v0, v85, s0
	v_mfma_f32_16x16x32_bf16 v[12:15], v[130:133], v[66:69], v[12:15]
	global_store_short v2, v0, s[2:3] offset:2048
	s_waitcnt vmcnt(16) lgkmcnt(0)
	s_barrier
	v_mfma_f32_16x16x32_bf16 v[8:11], v[154:157], v[66:69], v[8:11]
	v_mfma_f32_16x16x32_bf16 v[16:19], v[166:169], v[66:69], v[16:19]
	v_mfma_f32_16x16x32_bf16 v[20:23], v[174:177], v[66:69], v[20:23]
	v_mfma_f32_16x16x32_bf16 v[24:27], v[182:185], v[66:69], v[24:27]
	v_mfma_f32_16x16x32_bf16 v[28:31], v[190:193], v[66:69], v[28:31]
	s_waitcnt lgkmcnt(0)
	v_mfma_f32_16x16x32_bf16 v[32:35], v[198:201], v[66:69], v[32:35]
	s_mov_b64 s[6:7], 0x60000
	s_add_i32 s10, s10, 1
	v_lshl_add_u64 v[38:39], v[38:39], 0, s[6:7]
	s_and_b32 s11, s10, 1
	s_cmp_lg_u32 s10, 63
	s_cbranch_scc1 .Lscan_compute
	s_branch .LBB0_163
